# scan slice loop: gt/U waits moved from mid-step vmcnt(0) to loop top
# baseline (speedup 1.0000x reference)
; __device__ __forceinline__ float bflo(unsigned w) { return __uint_as_float(w << 16); }
; __device__ __forceinline__ float bfhi(unsigned w) { return __uint_as_float(w & 0xffff0000u); }
; __device__ __forceinline__ void scan_chain(const Params& P, bool smp, int s, int h, int sl, int lane) {
;     const int l15 = lane & 15, q4 = lane >> 4, e = 16 * sl + l15;
;     const int cu0 = smp ? 1024 + s : s * 128, nsteps = smp ? 1 : 128;
;     f32x4 S[4];
; #pragma unroll
;     for (int tau = 0; tau < 4; ++tau)
; #pragma unroll
;         for (int r = 0; r < 4; ++r) S[tau][r] = smp ? P.state_gdn[(((size_t)s * 8 + h) * 64 + 16 * tau + 4 * q4 + r) * 64 + e] : 0.f;
;     const float* GT = (const float*)(P.ws + WS_GT);
;     float* OA = (float*)((unsigned char*)P.out + YO_OA); float* OAS = (float*)(P.ws + WS_OAS);
; #pragma unroll 1
;     for (int n = 0; n < nsteps; ++n) {
;         const int cu = cu0 + n; const unsigned char* ops = P.ws + WS_OPS + ((size_t)cu * 8 + h) * OPS_UNIT;
;         const float gt = GT[cu * 8 + h];
;         const bf16x8* Wf = (const bf16x8*)(ops + OPS_W) + lane; const bf16x8* KT = (const bf16x8*)(ops + OPS_KT) + lane;
;         const bf16x8* QD = (const bf16x8*)(ops + OPS_QD) + lane; const bf16x8* QK = (const bf16x8*)(ops + OPS_QK) + lane;
;         const v2u* Up = (const v2u*)(ops + OPS_U) + (sl * 4) * 64 + lane;
;         bf16x8 Sb[2]; Sb[0] = pack8(S[0], S[1]); Sb[1] = pack8(S[2], S[3]);
;         f32x4 vn[4];
; #pragma unroll
;         for (int tau = 0; tau < 4; ++tau) { f32x4 av = {0.f, 0.f, 0.f, 0.f}; av = mfma16(Wf[(2 * tau) * 64], Sb[0], av); av = mfma16(Wf[(2 * tau + 1) * 64], Sb[1], av);
;             const v2u ub = Up[tau * 64]; const f32x4 u = {bflo(ub.x), bfhi(ub.x), bflo(ub.y), bfhi(ub.y)}; vn[tau] = u - av; }
;         bf16x8 Vb[2]; Vb[0] = pack8(vn[0], vn[1]); Vb[1] = pack8(vn[2], vn[3]);
;         f32x4 ao[4];
; #pragma unroll
;         for (int tau = 0; tau < 4; ++tau) { f32x4 a = {0.f, 0.f, 0.f, 0.f}; a = mfma16(QD[(2 * tau) * 64], Sb[0], a); a = mfma16(QD[(2 * tau + 1) * 64], Sb[1], a);
;             a = mfma16(QK[((tau < 2) ? tau : 2 * tau - 2) * 64], Vb[0], a); if (tau >= 2) a = mfma16(QK[(2 * tau - 1) * 64], Vb[1], a); ao[tau] = a; }
; #pragma unroll
;         for (int tau = 0; tau < 4; ++tau) { f32x4 a = S[tau] * gt; a = mfma16(KT[(2 * tau) * 64], Vb[0], a); a = mfma16(KT[(2 * tau + 1) * 64], Vb[1], a); S[tau] = a; }
.LBB0_639:
	v_readlane_b32 s18, v247, 0
	v_readlane_b32 s19, v247, 1
	s_add_u32 s29, s18, 0x1400000
	s_addc_u32 s30, s19, 0
	s_ashr_i32 s8, s96, 3
	s_lshl_b32 s0, s8, 7
	s_ashr_i32 s1, s0, 31
	s_and_b32 s2, s96, 7
	s_lshl_b64 s[14:15], s[0:1], 3
	s_add_u32 s10, s18, 0x3600000
	s_addc_u32 s11, s19, 0
	s_add_u32 s4, s18, 0xb700000
	s_addc_u32 s5, s19, 0
	s_ashr_i32 s9, s8, 31
	s_add_u32 s22, s18, 0x23900000
	s_addc_u32 s23, s19, 0
	s_or_b32 s12, s14, s2
	s_mul_i32 s13, s15, 0xa000
	s_mul_hi_u32 s16, s12, 0xa000
	s_add_i32 s16, s16, s13
	s_mul_i32 s12, s12, 0xa000
	s_add_u32 s12, s22, s12
	s_addc_u32 s13, s23, s16
	s_add_u32 s16, s18, 0x3d300000
	s_addc_u32 s17, s19, 0
	s_lshl_b32 s28, s96, 1
	s_ashr_i32 s18, s40, 8
	s_add_i32 s18, s18, s28
	s_ashr_i32 s26, s18, 3
	s_ashr_i32 s27, s26, 31
	s_and_b32 s34, s18, 7
	v_lshrrev_b32_e32 v1, 4, v164
	s_lshl_b64 s[18:19], s[26:27], 9
	v_and_b32_e32 v30, 15, v35
	v_lshl_or_b32 v2, v1, 2, s18
	s_bfe_u32 s24, s40, 0x20006
	v_lshl_or_b32 v2, s34, 6, v2
	v_mov_b32_e32 v3, s19
	v_lshlrev_b32_e32 v4, 2, v30
	v_mov_b32_e32 v165, 0
	v_lshl_or_b32 v4, s24, 6, v4
	v_mov_b32_e32 v5, v165
	v_lshlrev_b64 v[2:3], 8, v[2:3]
	v_lshl_add_u64 v[14:15], s[74:75], 0, v[4:5]
	v_or_b32_e32 v10, 0x1100, v2
	v_mov_b32_e32 v11, v3
	v_or_b32_e32 v8, 0x1000, v2
	v_mov_b32_e32 v9, v3
	v_lshl_add_u64 v[16:17], v[14:15], 0, v[10:11]
	v_or_b32_e32 v10, 0x1200, v2
	v_lshl_add_u64 v[6:7], v[14:15], 0, v[2:3]
	v_lshl_add_u64 v[8:9], v[14:15], 0, v[8:9]
	v_lshl_add_u64 v[18:19], v[14:15], 0, v[10:11]
	v_or_b32_e32 v10, 0x1300, v2
	s_add_i32 s18, s26, 0x400
	v_lshl_add_u64 v[20:21], v[14:15], 0, v[10:11]
	global_load_dword v10, v[6:7], off
	global_load_dword v11, v[6:7], off offset:256
	global_load_dword v12, v[6:7], off offset:512
	global_load_dword v13, v[6:7], off offset:768
	s_nop 0
	global_load_dword v6, v[8:9], off
	global_load_dword v7, v[16:17], off
	s_nop 0
	global_load_dword v8, v[18:19], off
	global_load_dword v9, v[20:21], off
	v_or_b32_e32 v18, 0x2100, v2
	v_mov_b32_e32 v19, v3
	s_ashr_i32 s19, s18, 31
	v_lshl_add_u64 v[22:23], v[14:15], 0, v[18:19]
	v_or_b32_e32 v18, 0x2200, v2
	s_lshl_b64 s[20:21], s[18:19], 3
	v_lshl_add_u64 v[28:29], v[14:15], 0, v[18:19]
	v_or_b32_e32 v18, 0x2300, v2
	s_or_b32 s19, s20, s34
	v_lshl_add_u64 v[32:33], v[14:15], 0, v[18:19]
	v_or_b32_e32 v18, 0x3000, v2
	s_mul_i32 s20, s21, 0xa000
	s_mul_hi_u32 s21, s19, 0xa000
	v_lshl_add_u64 v[36:37], v[14:15], 0, v[18:19]
	v_or_b32_e32 v18, 0x3100, v2
	s_add_i32 s21, s21, s20
	s_mul_i32 s19, s19, 0xa000
	v_or_b32_e32 v16, 0x2000, v2
	v_mov_b32_e32 v17, v3
	v_lshl_add_u64 v[38:39], v[14:15], 0, v[18:19]
	v_or_b32_e32 v18, 0x3200, v2
	s_add_u32 s20, s22, s19
	v_lshl_add_u64 v[16:17], v[14:15], 0, v[16:17]
	v_lshl_add_u64 v[40:41], v[14:15], 0, v[18:19]
	v_or_b32_e32 v2, 0x3300, v2
	s_addc_u32 s21, s23, s21
	v_lshlrev_b32_e32 v18, 4, v164
	v_lshl_add_u64 v[2:3], v[14:15], 0, v[2:3]
	global_load_dwordx4 v[24:27], v18, s[20:21]
	global_load_dword v20, v[16:17], off
	global_load_dword v21, v[22:23], off
	s_nop 0
	global_load_dword v22, v[28:29], off
	global_load_dword v23, v[32:33], off
	global_load_dword v14, v[36:37], off
	global_load_dword v15, v[38:39], off
	global_load_dword v16, v[40:41], off
	global_load_dword v17, v[2:3], off
	s_lshl_b32 s18, s18, 3
	global_load_dwordx4 v[36:39], v18, s[20:21] offset:1024
	global_load_dwordx4 v[40:43], v18, s[20:21] offset:2048
	s_or_b32 s18, s18, s34
	s_ashr_i32 s19, s18, 31
	s_lshl_b64 s[18:19], s[18:19], 2
	s_add_u32 s18, s29, s18
	s_addc_u32 s19, s30, s19
	s_lshl_b32 s22, s24, 11
	s_add_u32 s22, s20, s22
	s_addc_u32 s23, s21, 0
	v_lshlrev_b32_e32 v2, 3, v164
	v_mov_b32_e32 v3, v165
	v_lshl_add_u64 v[32:33], s[22:23], 0, v[2:3]
	s_mov_b32 s31, 0x8000
	v_mov_b32_e32 v19, v165
	v_add_co_u32_e32 v44, vcc, s31, v32
	s_movk_i32 s36, 0x2000
	v_lshl_add_u64 v[28:29], s[20:21], 0, v[18:19]
	v_addc_co_u32_e32 v45, vcc, 0, v33, vcc
	v_add_co_u32_e32 v82, vcc, s36, v28
	global_load_dwordx2 v[96:97], v[44:45], off
	s_nop 0
	global_load_dwordx4 v[44:47], v18, s[20:21] offset:3072
	v_addc_co_u32_e32 v83, vcc, 0, v29, vcc
	global_load_dwordx4 v[48:51], v[82:83], off offset:-4096
	s_movk_i32 s35, 0x1000
	v_add_co_u32_e32 v60, vcc, s35, v28
	s_mov_b64 s[24:25], 0x8000
	s_nop 0
	v_addc_co_u32_e32 v61, vcc, 0, v29, vcc
	global_load_dwordx4 v[52:55], v[60:61], off offset:1024
	v_lshl_add_u64 v[32:33], v[32:33], 0, s[24:25]
	global_load_dwordx2 v[98:99], v[32:33], off offset:512
	global_load_dwordx4 v[56:59], v[60:61], off offset:2048
	s_nop 0
	global_load_dwordx4 v[60:63], v[60:61], off offset:3072
	s_movk_i32 s22, 0x4000
	s_mov_b64 s[20:21], 0x4000
	v_add_co_u32_e32 v64, vcc, s22, v28
	v_lshl_add_u64 v[68:69], v[28:29], 0, s[20:21]
	s_nop 0
	v_addc_co_u32_e32 v65, vcc, 0, v29, vcc
	s_movk_i32 s20, 0x6000
	v_add_co_u32_e32 v72, vcc, s20, v28
	global_load_dwordx4 v[64:67], v[64:65], off
	s_nop 0
	v_addc_co_u32_e32 v73, vcc, 0, v29, vcc
	global_load_dwordx4 v[68:71], v[68:69], off offset:1024
	s_nop 0
	global_load_dwordx4 v[72:75], v[72:73], off
	s_nop 0
	global_load_dwordx2 v[100:101], v[32:33], off offset:1024
	s_nop 0
	global_load_dwordx2 v[32:33], v[32:33], off offset:1536
	s_nop 0
	global_load_dword v34, v165, s[18:19]
	s_waitcnt vmcnt(30)
	v_cvt_pk_bf16_f32 v76, v10, v11
	s_waitcnt vmcnt(28)
	v_cvt_pk_bf16_f32 v77, v12, v13
	s_waitcnt vmcnt(26)
	v_cvt_pk_bf16_f32 v78, v6, v7
	s_waitcnt vmcnt(24)
	v_cvt_pk_bf16_f32 v79, v8, v9
	s_mov_b64 s[18:19], 0x2000
	v_lshl_add_u64 v[92:93], v[28:29], 0, s[18:19]
	s_waitcnt vmcnt(23)
	v_mfma_f32_16x16x32_bf16 v[24:27], v[24:27], v[76:79], 0
	global_load_dwordx4 v[84:87], v[82:83], off
	global_load_dwordx4 v[88:91], v[92:93], off offset:1024
	s_waitcnt vmcnt(23)
; __device__ __forceinline__ float bflo(unsigned w) { return __uint_as_float(w << 16); }
; __device__ __forceinline__ void scan_chain(const Params& P, bool smp, int s, int h, int sl, int lane) {
;     ...
;         for (int tau = 0; tau < 4; ++tau) { f32x4 av = {0.f, 0.f, 0.f, 0.f}; av = mfma16(Wf[(2 * tau) * 64], Sb[0], av); av = mfma16(Wf[(2 * tau + 1) * 64], Sb[1], av);
;             const v2u ub = Up[tau * 64]; const f32x4 u = {bflo(ub.x), bfhi(ub.x), bflo(ub.y), bfhi(ub.y)}; vn[tau] = u - av; }
;         bf16x8 Vb[2]; Vb[0] = pack8(vn[0], vn[1]); Vb[1] = pack8(vn[2], vn[3]);
;         f32x4 ao[4];
; #pragma unroll
;         for (int tau = 0; tau < 4; ++tau) { f32x4 a = {0.f, 0.f, 0.f, 0.f}; a = mfma16(QD[(2 * tau) * 64], Sb[0], a); a = mfma16(QD[(2 * tau + 1) * 64], Sb[1], a);
;             a = mfma16(QK[((tau < 2) ? tau : 2 * tau - 2) * 64], Vb[0], a); if (tau >= 2) a = mfma16(QK[(2 * tau - 1) * 64], Vb[1], a); ao[tau] = a; }
; #pragma unroll
;         for (int tau = 0; tau < 4; ++tau) { f32x4 a = S[tau] * gt; a = mfma16(KT[(2 * tau) * 64], Vb[0], a); a = mfma16(KT[(2 * tau + 1) * 64], Vb[1], a); S[tau] = a; }
;         if (!smp) { float* op = OA + ((size_t)s * TP + n * 64) * 512 + h * 64 + e;
; #pragma unroll
;             for (int tau = 0; tau < 4; ++tau)
; #pragma unroll
;                 for (int r = 0; r < 4; ++r) op[(size_t)(16 * tau + 4 * q4 + r) * 512] = ao[tau][r];
;         } else { float* op = OAS + ((size_t)s * 16) * 512 + h * 64 + e;
; #pragma unroll
;             for (int r = 0; r < 4; ++r) op[(size_t)(4 * q4 + r) * 512] = ao[0][r]; }
;     }
;     float* so = P.out + (smp ? O_GS : O_GP) + (((size_t)s * 8 + h) * 64) * 64 + e;
; #pragma unroll
;     for (int tau = 0; tau < 4; ++tau)
; #pragma unroll
;         for (int r = 0; r < 4; ++r) so[(size_t)(16 * tau + 4 * q4 + r) * 64] = S[tau][r];
; __global__ void __launch_bounds__(NWAVES * 64, 2) fwd_kernel(Params P) {
;     ...
;             asm volatile("s_waitcnt vmcnt(0)" ::: "memory"); __syncthreads();
;             {
;                 const int pr = (int)blockIdx.x * 2 + (tid >> 8), sp = pr >> 3, hp_ = pr & 7, t = (tid >> 4) & 15, part = tid & 15;
;                 const size_t row = (size_t)sp * 16 + t;
;                 const f32x4 o4 = *(const f32x4*)((const float*)(ws + WS_OAS) + row * 512 + hp_ * 64 + 4 * part);
	v_cvt_pk_bf16_f32 v80, v20, v21
	s_waitcnt vmcnt(21)
	v_cvt_pk_bf16_f32 v81, v22, v23
	s_waitcnt vmcnt(15)
	v_mfma_f32_16x16x32_bf16 v[40:43], v[40:43], v[76:79], 0
	v_cvt_pk_bf16_f32 v82, v14, v15
	v_cvt_pk_bf16_f32 v83, v16, v17
	s_movk_i32 s18, 0x3000
	v_readlane_b32 s72, v247, 7
	v_mfma_f32_16x16x32_bf16 v[24:27], v[36:39], v[80:83], v[24:27]
	global_load_dwordx4 v[36:39], v[92:93], off offset:2048
	v_readlane_b32 s82, v247, 17
	global_load_dwordx4 v[92:95], v[92:93], off offset:3072
	s_waitcnt vmcnt(15)
	v_mfma_f32_16x16x32_bf16 v[40:43], v[44:47], v[80:83], v[40:43]
	v_lshlrev_b32_e32 v19, 16, v96
	v_and_b32_e32 v31, 0xffff0000, v96
	s_nop 0
	v_sub_f32_e32 v31, v31, v25
	s_waitcnt vmcnt(14)
	v_mfma_f32_16x16x32_bf16 v[44:47], v[48:51], v[76:79], 0
	v_lshlrev_b32_e32 v48, 16, v97
	v_and_b32_e32 v49, 0xffff0000, v97
	v_sub_f32_e32 v96, v49, v27
	s_waitcnt vmcnt(13)
	v_mfma_f32_16x16x32_bf16 v[44:47], v[52:55], v[80:83], v[44:47]
	v_sub_f32_e32 v52, v48, v26
	v_sub_f32_e32 v19, v19, v24
	s_waitcnt vmcnt(12)
	v_lshlrev_b32_e32 v53, 16, v98
	s_waitcnt vmcnt(11)
	v_mfma_f32_16x16x32_bf16 v[24:27], v[56:59], v[76:79], 0
	v_and_b32_e32 v54, 0xffff0000, v98
	v_lshlrev_b32_e32 v48, 16, v99
	v_sub_f32_e32 v53, v53, v40
	s_waitcnt vmcnt(10)
	v_mfma_f32_16x16x32_bf16 v[24:27], v[60:63], v[80:83], v[24:27]
	v_cvt_pk_bf16_f32 v40, v19, v31
	v_sub_f32_e32 v55, v48, v42
	s_waitcnt vmcnt(6)
	v_lshlrev_b32_e32 v19, 16, v100
	v_and_b32_e32 v31, 0xffff0000, v100
	v_sub_f32_e32 v42, v54, v41
	v_sub_f32_e32 v31, v31, v45
	v_sub_f32_e32 v19, v19, v44
	v_cvt_pk_bf16_f32 v41, v52, v96
	v_cvt_pk_bf16_f32 v42, v53, v42
	v_lshlrev_b32_e32 v52, 16, v101
	v_and_b32_e32 v53, 0xffff0000, v101
	v_cvt_pk_bf16_f32 v44, v19, v31
	s_waitcnt vmcnt(5)
	v_lshlrev_b32_e32 v19, 16, v32
	v_and_b32_e32 v31, 0xffff0000, v32
	v_lshlrev_b32_e32 v32, 16, v33
	v_sub_f32_e32 v47, v53, v47
	v_sub_f32_e32 v46, v52, v46
	v_and_b32_e32 v33, 0xffff0000, v33
	v_sub_f32_e32 v52, v32, v26
	v_add_co_u32_e32 v32, vcc, s18, v28
	v_cvt_pk_bf16_f32 v45, v46, v47
	v_sub_f32_e32 v47, v33, v27
	v_addc_co_u32_e32 v33, vcc, 0, v29, vcc
	global_load_dwordx4 v[26:29], v[32:33], off offset:3072
	global_load_dwordx4 v[56:59], v[32:33], off offset:2048
	v_and_b32_e32 v49, 0xffff0000, v99
	v_sub_f32_e32 v43, v49, v43
	v_cvt_pk_bf16_f32 v43, v55, v43
	v_cvt_pk_bf16_f32 v47, v52, v47
	global_load_dwordx4 v[52:55], v[32:33], off
	s_waitcnt vmcnt(7)
	v_pk_mul_f32 v[8:9], v[8:9], v[34:35] op_sel_hi:[1,0]
	v_pk_mul_f32 v[6:7], v[6:7], v[34:35] op_sel_hi:[1,0]
	v_mfma_f32_16x16x32_bf16 v[48:51], v[64:67], v[76:79], 0
	s_lshl_b64 s[18:19], s[26:27], 15
	s_add_u32 s18, s16, s18
	v_pk_mul_f32 v[16:17], v[16:17], v[34:35] op_sel_hi:[1,0]
	s_waitcnt vmcnt(4)
	v_mfma_f32_16x16x32_bf16 v[6:9], v[36:39], v[40:43], v[6:9]
	global_load_dwordx4 v[36:39], v[32:33], off offset:1024
	v_pk_mul_f32 v[14:15], v[14:15], v[34:35] op_sel_hi:[1,0]
	s_addc_u32 s19, s17, s19
	v_mfma_f32_16x16x32_bf16 v[48:51], v[68:71], v[80:83], v[48:51]
	s_lshl_b32 s20, s34, 8
	s_add_u32 s18, s18, s20
	v_sub_f32_e32 v25, v31, v25
	s_waitcnt vmcnt(2)
	v_mfma_f32_16x16x32_bf16 v[14:17], v[56:59], v[40:43], v[14:17]
	v_sub_f32_e32 v19, v19, v24
	s_addc_u32 s19, s19, 0
	v_cvt_pk_bf16_f32 v46, v19, v25
	v_mfma_f32_16x16x32_bf16 v[48:51], v[72:75], v[40:43], v[48:51]
	v_lshl_add_u64 v[24:25], s[18:19], 0, v[4:5]
	s_lshl_b64 s[18:19], s[26:27], 17
	v_pk_mul_f32 v[12:13], v[12:13], v[34:35] op_sel_hi:[1,0]
	v_pk_mul_f32 v[10:11], v[10:11], v[34:35] op_sel_hi:[1,0]
	v_mfma_f32_16x16x32_bf16 v[14:17], v[26:29], v[44:47], v[14:17]
	v_lshlrev_b32_e32 v26, 13, v1
	v_mov_b32_e32 v27, v165
	s_add_u32 s18, s54, s18
	v_mfma_f32_16x16x32_bf16 v[10:13], v[84:87], v[40:43], v[10:13]
	v_lshl_add_u64 v[24:25], v[24:25], 0, v[26:27]
	s_addc_u32 s19, s55, s19
	s_lshl_b32 s20, s34, 14
	global_store_dword v[24:25], v48, off
	global_store_dword v[24:25], v49, off offset:2048
	v_add_co_u32_e32 v24, vcc, s35, v24
	s_add_u32 s18, s18, s20
	s_nop 0
	v_addc_co_u32_e32 v25, vcc, 0, v25, vcc
	s_addc_u32 s19, s19, 0
	v_pk_mul_f32 v[22:23], v[22:23], v[34:35] op_sel_hi:[1,0]
	v_pk_mul_f32 v[20:21], v[20:21], v[34:35] op_sel_hi:[1,0]
	global_store_dword v[24:25], v50, off
	global_store_dword v[24:25], v51, off offset:2048
	v_lshl_add_u64 v[4:5], s[18:19], 0, v[4:5]
	v_lshlrev_b32_e32 v24, 10, v1
	v_mov_b32_e32 v25, v165
	v_mfma_f32_16x16x32_bf16 v[10:13], v[88:91], v[44:47], v[10:13]
	v_lshl_add_u64 v[4:5], v[4:5], 0, v[24:25]
	s_mov_b64 s[18:19], 0x1126c000
	v_lshl_add_u64 v[24:25], v[4:5], 0, s[18:19]
	s_waitcnt vmcnt(5)
	v_mfma_f32_16x16x32_bf16 v[20:23], v[52:55], v[40:43], v[20:23]
	s_mov_b32 s18, 0x1126d000
	v_add_co_u32_e32 v26, vcc, s18, v4
	v_mfma_f32_16x16x32_bf16 v[6:9], v[92:95], v[44:47], v[6:9]
	s_nop 0
	v_addc_co_u32_e32 v27, vcc, 0, v5, vcc
	s_mov_b32 s18, 0x1126e000
	s_waitcnt vmcnt(4)
	v_mfma_f32_16x16x32_bf16 v[20:23], v[36:39], v[44:47], v[20:23]
	global_store_dword v[26:27], v10, off offset:-4096
	global_store_dword v[24:25], v11, off offset:256
	global_store_dword v[24:25], v12, off offset:512
	global_store_dword v[24:25], v13, off offset:768
	global_store_dword v[26:27], v6, off
	global_store_dword v[26:27], v7, off offset:256
	global_store_dword v[26:27], v8, off offset:512
	global_store_dword v[26:27], v9, off offset:768
	v_add_co_u32_e32 v6, vcc, s18, v4
	s_mov_b32 s18, 0x1126f000
	s_nop 0
	v_addc_co_u32_e32 v7, vcc, 0, v5, vcc
	v_add_co_u32_e32 v4, vcc, s18, v4
	v_ashrrev_i32_e32 v1, 8, v35
	s_nop 0
	v_addc_co_u32_e32 v5, vcc, 0, v5, vcc
	v_add_u32_e32 v1, s28, v1
	global_store_dword v[4:5], v20, off offset:-4096
	global_store_dword v[6:7], v21, off offset:256
	global_store_dword v[6:7], v22, off offset:512
	global_store_dword v[6:7], v23, off offset:768
	global_store_dword v[4:5], v14, off
	global_store_dword v[4:5], v15, off offset:256
	global_store_dword v[4:5], v16, off offset:512
	global_store_dword v[4:5], v17, off offset:768
	v_ashrrev_i32_e32 v4, 3, v1
	v_ashrrev_i32_e32 v5, 31, v4
	v_lshrrev_b32_e32 v6, 4, v35
	v_lshlrev_b64 v[8:9], 4, v[4:5]
	v_and_or_b32 v8, v6, 15, v8
	v_lshlrev_b32_e32 v1, 6, v1
	v_lshlrev_b64 v[4:5], 11, v[8:9]
	v_and_b32_e32 v1, 0x1c0, v1
	v_lshl_add_u64 v[4:5], s[16:17], 0, v[4:5]
	v_lshlrev_b32_e32 v6, 2, v1
	v_mov_b32_e32 v7, v165
	v_lshl_add_u64 v[4:5], v[4:5], 0, v[6:7]
	v_lshlrev_b32_e32 v6, 2, v35
	v_and_b32_e32 v12, 60, v6
	v_lshlrev_b32_e32 v10, 2, v12
	v_mov_b32_e32 v11, v165
	v_lshl_add_u64 v[4:5], v[4:5], 0, v[10:11]
	s_waitcnt vmcnt(0)
	s_barrier
; __device__ __forceinline__ unsigned pk2(float lo, float hi) { return pg8::cvt_pk_bf16_v(lo, hi); }
; __device__ __forceinline__ float bflo(unsigned w) { return __uint_as_float(w << 16); }
; __device__ __forceinline__ float bfhi(unsigned w) { return __uint_as_float(w & 0xffff0000u); }
; __device__ __forceinline__ void scan_prompt_wg(const Params& P, LAS unsigned char* lds, int s, int h, int wave, int lane) {
;     ...
;         const int sl = wave, l15 = lane & 15, q4 = lane >> 4, e = 16 * sl + l15;
;         f32x4 S[4];
; #pragma unroll
;         for (int tau = 0; tau < 4; ++tau) S[tau] = (f32x4){0.f, 0.f, 0.f, 0.f};
;         const float* GT = (const float*)(P.ws + WS_GT) + (size_t)(s * 128) * 8 + h;
;         const v2u* Ug = (const v2u*)(ops0 + OPS_U) + (sl * 4) * 64 + lane;
;         v2u ua[4], ub[4];
; #pragma unroll
;         for (int tau = 0; tau < 4; ++tau) { ua[tau] = Ug[tau * 64]; ub[tau] = (Ug + step_stride / 8)[tau * 64]; }
;         SCAN_BAR();
;         int slot = 0;
;         float gt = GT[0];
; __global__ void __launch_bounds__(NWAVES * 64, 2) fwd_kernel(Params P) {
;     ...
;                 const int pr = (int)blockIdx.x * 2 + (tid >> 8), sp = pr >> 3, hp_ = pr & 7, t = (tid >> 4) & 15, part = tid & 15;
;                 const size_t row = (size_t)sp * 16 + t;
;                 const f32x4 o4 = *(const f32x4*)((const float*)(ws + WS_OAS) + row * 512 + hp_ * 64 + 4 * part);
;                 float ss = (o4[0] * o4[0] + o4[1] * o4[1]) + (o4[2] * o4[2] + o4[3] * o4[3]);
;                 ss += __shfl_xor(ss, 1); ss += __shfl_xor(ss, 2); ss += __shfl_xor(ss, 4); ss += __shfl_xor(ss, 8);
;                 const float rstd = __builtin_amdgcn_rsqf(ss * (1.0f / 64.0f) + 1e-6f);
;                 const size_t mo = ((size_t)MP + row) * 1024 + hp_ * 64 + 4 * part;
;                 const v2u zb = *(const v2u*)((const bf16*)(ws + WS_Z) + mo);
;                 const f32x4 g4 = *(const f32x4*)(P.gdn_g + 4 * part);
;                 v2u o; o.x = pk2(o4[0] * rstd * g4[0] * siluf(bflo(zb.x)), o4[1] * rstd * g4[1] * siluf(bfhi(zb.x))); o.y = pk2(o4[2] * rstd * g4[2] * siluf(bflo(zb.y)), o4[3] * rstd * g4[3] * siluf(bfhi(zb.y)));
;                 *(v2u*)((bf16*)(ws + WS_MIX) + mo) = o;
;             }
;             __syncthreads();
;             REP(30) { scan_prompt_wg(P, lds, (int)blockIdx.x >> 3, (int)blockIdx.x & 7, wave, lane); __syncthreads(); }
	global_load_dwordx4 v[4:7], v[4:5], off
	v_lshlrev_b64 v[8:9], 10, v[8:9]
	v_or3_b32 v8, v8, v1, v12
	v_mov_b64_e32 v[12:13], 0x8000000
	v_lshl_add_u64 v[12:13], v[8:9], 1, v[12:13]
	v_lshl_add_u64 v[8:9], s[10:11], 0, v[12:13]
	global_load_dwordx2 v[14:15], v[8:9], off
	v_readlane_b32 s83, v247, 18
	v_mbcnt_lo_u32_b32 v1, -1, 0
	v_mbcnt_hi_u32_b32 v1, -1, v1
	v_xor_b32_e32 v53, 1, v1
	v_xor_b32_e32 v54, 2, v1
	v_xor_b32_e32 v55, 4, v1
	global_load_dwordx4 v[8:11], v10, s[82:83]
	v_xor_b32_e32 v56, 8, v1
	v_mov_b32_e32 v19, 0x358637bd
	s_mov_b64 s[46:47], s[82:83]
	s_mov_b64 s[16:17], -1
	s_cmp_lt_i32 s33, 4
	s_mul_hi_i32 s26, s0, 0x50000
	s_mul_i32 s27, s0, 0x50000
	s_mul_i32 s28, s2, 0xa000
	v_readlane_b32 s73, v247, 8
	v_readlane_b32 s74, v247, 9
	v_readlane_b32 s75, v247, 10
	v_readlane_b32 s76, v247, 11
	v_readlane_b32 s77, v247, 12
	v_readlane_b32 s78, v247, 13
	v_readlane_b32 s79, v247, 14
	v_readlane_b32 s80, v247, 15
	v_readlane_b32 s81, v247, 16
	v_readlane_b32 s84, v247, 19
	v_readlane_b32 s85, v247, 20
	v_readlane_b32 s86, v247, 21
	v_readlane_b32 s87, v247, 22
	s_waitcnt vmcnt(2)
	v_pk_mul_f32 v[16:17], v[6:7], v[6:7]
	v_pk_mul_f32 v[20:21], v[4:5], v[4:5]
	s_nop 0
	v_pk_mov_b32 v[22:23], v[20:21], v[16:17] op_sel:[1,0]
	v_mov_b32_e32 v21, v17
	v_pk_add_f32 v[16:17], v[22:23], v[20:21]
	s_nop 0
	v_add_f32_e32 v16, v16, v17
	v_and_b32_e32 v17, 64, v1
	v_add_u32_e32 v52, 64, v17
	v_cmp_lt_i32_e32 vcc, v53, v52
	s_nop 1
	v_cndmask_b32_e32 v17, v1, v53, vcc
	v_lshlrev_b32_e32 v57, 2, v17
	ds_bpermute_b32 v17, v57, v16
	v_cmp_lt_i32_e32 vcc, v54, v52
	s_waitcnt lgkmcnt(0)
	v_add_f32_e32 v16, v16, v17
	v_cndmask_b32_e32 v17, v1, v54, vcc
	v_lshlrev_b32_e32 v58, 2, v17
	ds_bpermute_b32 v17, v58, v16
	v_cmp_lt_i32_e32 vcc, v55, v52
	s_waitcnt lgkmcnt(0)
	v_add_f32_e32 v16, v16, v17
	v_cndmask_b32_e32 v17, v1, v55, vcc
	v_lshlrev_b32_e32 v17, 2, v17
	ds_bpermute_b32 v17, v17, v16
	v_cmp_lt_i32_e32 vcc, v56, v52
	s_waitcnt lgkmcnt(0)
	v_add_f32_e32 v16, v16, v17
	v_cndmask_b32_e32 v17, v1, v56, vcc
	v_lshlrev_b32_e32 v17, 2, v17
	ds_bpermute_b32 v17, v17, v16
	s_waitcnt lgkmcnt(0)
	v_add_f32_e32 v16, v16, v17
	v_fmac_f32_e32 v19, 0x3c800000, v16
	s_waitcnt vmcnt(1)
	v_lshlrev_b32_e32 v16, 16, v14
	v_and_b32_e32 v17, 0xffff0000, v14
	v_mul_f32_e32 v14, 0xbfb8aa3b, v16
	v_exp_f32_e32 v20, v14
	v_mul_f32_e32 v14, 0xbfb8aa3b, v17
	v_exp_f32_e32 v21, v14
	v_rsq_f32_e32 v14, v19
	v_add_f32_e32 v19, 1.0, v20
	v_rcp_f32_e32 v20, v19
	v_add_f32_e32 v19, 1.0, v21
	v_rcp_f32_e32 v21, v19
	v_pk_mul_f32 v[4:5], v[4:5], v[14:15] op_sel_hi:[1,0]
	s_waitcnt vmcnt(0)
	v_pk_mul_f32 v[4:5], v[8:9], v[4:5]
	v_pk_mul_f32 v[8:9], v[20:21], v[16:17]
	v_lshlrev_b32_e32 v16, 16, v15
	v_and_b32_e32 v17, 0xffff0000, v15
	v_mul_f32_e32 v15, 0xbfb8aa3b, v16
	v_mul_f32_e32 v19, 0xbfb8aa3b, v17
	v_exp_f32_e32 v15, v15
	v_exp_f32_e32 v19, v19
	v_pk_mul_f32 v[4:5], v[4:5], v[8:9]
	v_add_f32_e32 v8, 1.0, v15
	v_add_f32_e32 v9, 1.0, v19
	v_rcp_f32_e32 v8, v8
	v_rcp_f32_e32 v9, v9
	v_pk_mul_f32 v[6:7], v[6:7], v[14:15] op_sel_hi:[1,0]
	v_cvt_pk_bf16_f32 v4, v4, v5
	v_pk_mul_f32 v[6:7], v[10:11], v[6:7]
	v_pk_mul_f32 v[8:9], v[8:9], v[16:17]
	s_nop 0
	v_pk_mul_f32 v[6:7], v[6:7], v[8:9]
	s_nop 0
	v_cvt_pk_bf16_f32 v5, v6, v7
	v_lshl_add_u64 v[6:7], s[4:5], 0, v[12:13]
	global_store_dwordx2 v[6:7], v[4:5], off
	s_barrier
	s_cbranch_scc0 .LBB0_654
	s_lshl_b32 s16, s33, 8
	s_ashr_i32 s17, s16, 31
	s_lshl_b64 s[16:17], s[16:17], 3
	s_add_u32 s18, s12, s16
	s_addc_u32 s19, s13, s17
	v_lshl_add_u64 v[4:5], s[18:19], 0, v[2:3]
	v_add_co_u32_e32 v8, vcc, s31, v4
	s_mov_b32 s19, 0x58000
	s_nop 0
	v_addc_co_u32_e32 v9, vcc, 0, v5, vcc
	v_lshl_add_u64 v[6:7], v[4:5], 0, s[24:25]
	v_add_co_u32_e32 v4, vcc, s19, v4
	s_lshl_b64 s[14:15], s[14:15], 2
	s_nop 0
	v_addc_co_u32_e32 v5, vcc, 0, v5, vcc
	global_load_dwordx2 v[50:51], v[8:9], off
	global_load_dwordx2 v[48:49], v[6:7], off offset:512
	global_load_dwordx2 v[46:47], v[6:7], off offset:1024
	global_load_dwordx2 v[44:45], v[6:7], off offset:1536
	global_load_dwordx2 v[22:23], v[4:5], off
	global_load_dwordx2 v[24:25], v[4:5], off offset:512
	global_load_dwordx2 v[26:27], v[4:5], off offset:1024
	global_load_dwordx2 v[28:29], v[4:5], off offset:1536
	s_add_u32 s14, s29, s14
	s_addc_u32 s15, s30, s15
	s_lshl_b32 s18, s2, 2
	s_barrier
	v_mov_b32_e32 v4, s18
	global_load_dword v91, v4, s[14:15]
	s_lshl_b64 s[0:1], s[0:1], 5
	s_or_b32 s0, s0, s18
	v_readlane_b32 s18, v247, 0
	v_readlane_b32 s19, v247, 1
	s_add_u32 s0, s18, s0
	s_addc_u32 s1, s19, s1
	s_add_u32 s14, s0, 0x1400020
	s_addc_u32 s15, s1, 0
	s_add_u32 s0, s27, s28
	s_addc_u32 s1, s26, 0
	s_add_u32 s0, s0, s16
	s_addc_u32 s1, s1, s17
	v_lshrrev_b32_e32 v4, 2, v164
	s_add_u32 s0, s18, s0
	v_and_b32_e32 v73, 12, v4
	s_addc_u32 s1, s19, s1
	v_lshl_or_b32 v20, s33, 4, v30
	v_or_b32_e32 v72, 1, v73
	v_or_b32_e32 v71, 2, v73
	v_or_b32_e32 v70, 3, v4
	v_or_b32_e32 v69, 16, v73
	v_or_b32_e32 v68, 17, v73
	v_or_b32_e32 v67, 18, v73
	v_or_b32_e32 v66, 19, v4
	v_or_b32_e32 v65, 32, v73
	v_or_b32_e32 v64, 33, v73
	v_or_b32_e32 v63, 34, v73
	v_or_b32_e32 v62, 35, v4
	v_or_b32_e32 v61, 48, v73
	v_or_b32_e32 v60, 49, v73
	v_or_b32_e32 v59, 50, v73
	v_or_b32_e32 v19, 51, v4
	v_lshl_add_u64 v[2:3], s[0:1], 0, v[2:3]
	s_mov_b64 s[0:1], 0x239a8400
	s_mov_b32 s31, 0
	v_lshl_add_u32 v21, v20, 1, 0
	v_lshlrev_b32_e32 v74, 7, v73
	v_lshlrev_b32_e32 v75, 7, v72
	v_lshlrev_b32_e32 v76, 7, v71
	v_lshlrev_b32_e32 v77, 7, v70
	v_lshlrev_b32_e32 v78, 7, v69
	v_lshlrev_b32_e32 v79, 7, v68
	v_lshlrev_b32_e32 v80, 7, v67
	v_lshlrev_b32_e32 v81, 7, v66
	v_lshlrev_b32_e32 v82, 7, v65
	v_lshlrev_b32_e32 v83, 7, v64
	v_lshlrev_b32_e32 v84, 7, v63
	v_lshlrev_b32_e32 v85, 7, v62
	v_lshlrev_b32_e32 v86, 7, v61
	v_lshlrev_b32_e32 v87, 7, v60
	v_lshlrev_b32_e32 v88, 7, v59
	v_lshlrev_b32_e32 v89, 7, v19
	v_lshl_add_u32 v90, v164, 4, 0
	v_lshl_add_u64 v[30:31], v[2:3], 0, s[0:1]
	s_mov_b32 s29, 0x1e000
	s_mov_b64 s[16:17], 0x50000
	v_mov_b32_e32 v32, 0
	s_mov_b32 s30, 0
	v_mov_b32_e32 v14, v165
	v_mov_b32_e32 v15, v165
	v_mov_b32_e32 v16, v165
	v_mov_b32_e32 v17, v165
	v_mov_b32_e32 v10, v165
	v_mov_b32_e32 v11, v165
	v_mov_b32_e32 v12, v165
	v_mov_b32_e32 v13, v165
	v_mov_b32_e32 v2, v165
	v_mov_b32_e32 v3, v165
	v_mov_b32_e32 v4, v165
	v_mov_b32_e32 v5, v165
	v_mov_b32_e32 v6, v165
	v_mov_b32_e32 v7, v165
	v_mov_b32_e32 v8, v165
	v_mov_b32_e32 v9, v165
	s_branch .LBB0_643

; __device__ __forceinline__ void scan_prompt_wg(const Params& P, LAS unsigned char* lds, int s, int h, int wave, int lane) {
;     ...
;         for (int n = 0; n < NST; ++n) {
;             const LAS unsigned char* ops = lds + slot * SR_SLOT;
;             const float gtn = (n + 1 < NST) ? GT[(size_t)(n + 1) * 8] : 0.f;
;             v2u uc[4];
; #pragma unroll
;             for (int tau = 0; tau < 4; ++tau) uc[tau] = (n + 2 < NST) ? (Ug + (size_t)(n + 2) * (step_stride / 8))[tau * 64] : (v2u){0u, 0u};
;             const LAS bf16x8* Wf = (const LAS bf16x8*)(ops + OPS_W) + lane; const LAS bf16x8* KT = (const LAS bf16x8*)(ops + OPS_KT) + lane;
;             const LAS bf16x8* QD = (const LAS bf16x8*)(ops + OPS_QD) + lane; const LAS bf16x8* QK = (const LAS bf16x8*)(ops + OPS_QK) + lane;
;             bf16x8 wv[8], qdv[8], qkv[6], ktv[8];
; #pragma unroll
;             for (int i = 0; i < 8; ++i) wv[i] = Wf[i * 64];
; #pragma unroll
;             for (int i = 0; i < 8; ++i) qdv[i] = QD[i * 64];
; #pragma unroll
;             for (int i = 0; i < 6; ++i) qkv[i] = QK[i * 64];
; #pragma unroll
;             for (int i = 0; i < 8; ++i) ktv[i] = KT[i * 64];
;             __builtin_amdgcn_sched_barrier(0);
;             bf16x8 Sb[2]; Sb[0] = pack8(S[0], S[1]); Sb[1] = pack8(S[2], S[3]);
;             f32x4 vn[4];
; #pragma unroll
;             for (int tau = 0; tau < 4; ++tau) { f32x4 av = {0.f, 0.f, 0.f, 0.f}; av = mfma16(wv[2 * tau], Sb[0], av); av = mfma16(wv[2 * tau + 1], Sb[1], av);
;                 const f32x4 u = {bflo(ua[tau].x), bfhi(ua[tau].x), bflo(ua[tau].y), bfhi(ua[tau].y)}; vn[tau] = u - av; }
;             bf16x8 Vb[2]; Vb[0] = pack8(vn[0], vn[1]); Vb[1] = pack8(vn[2], vn[3]);
;             f32x4 ao[4];
; #pragma unroll
;             for (int tau = 0; tau < 4; ++tau) { f32x4 a = {0.f, 0.f, 0.f, 0.f}; a = mfma16(qdv[2 * tau], Sb[0], a); a = mfma16(qdv[2 * tau + 1], Sb[1], a);
;                 a = mfma16(qkv[(tau < 2) ? tau : 2 * tau - 2], Vb[0], a); if (tau >= 2) a = mfma16(qkv[2 * tau - 1], Vb[1], a); ao[tau] = a; }
; #pragma unroll
;             for (int tau = 0; tau < 4; ++tau) { f32x4 a = S[tau] * gt; a = mfma16(ktv[2 * tau], Vb[0], a); a = mfma16(ktv[2 * tau + 1], Vb[1], a); S[tau] = a; }
;             LAS unsigned char* ot = lds + ((n & 1) ? OT_B : OT_A) + e * 2;
; #pragma unroll
;             for (int tau = 0; tau < 4; ++tau)
; #pragma unroll
.LBB0_642:
	s_mul_i32 s0, s30, 0x7800
	v_add_u32_e32 v33, s0, v90
	ds_read_b128 v[92:95], v33
	ds_read_b128 v[96:99], v33 offset:1024
	ds_read_b128 v[100:103], v33 offset:2048
	ds_read_b128 v[104:107], v33 offset:3072
	ds_read_b128 v[108:111], v33 offset:4096
	ds_read_b128 v[112:115], v33 offset:5120
	ds_read_b128 v[116:119], v33 offset:6144
	ds_read_b128 v[120:123], v33 offset:7168
	ds_read_b128 v[124:127], v33 offset:16384
	ds_read_b128 v[128:131], v33 offset:17408
	ds_read_b128 v[132:135], v33 offset:18432
	ds_read_b128 v[136:139], v33 offset:19456
	ds_read_b128 v[140:143], v33 offset:20480
	ds_read_b128 v[144:147], v33 offset:21504
	ds_read_b128 v[148:151], v33 offset:22528
	ds_read_b128 v[152:155], v33 offset:23552
	ds_read_b128 v[156:159], v33 offset:24576
	ds_read_b128 v[160:163], v33 offset:25600
	ds_read_b128 v[166:169], v33 offset:26624
	ds_read_b128 v[170:173], v33 offset:27648
	ds_read_b128 v[174:177], v33 offset:28672
	ds_read_b128 v[178:181], v33 offset:29696
	ds_read_b128 v[182:185], v33 offset:8192
	ds_read_b128 v[186:189], v33 offset:9216
	ds_read_b128 v[190:193], v33 offset:10240
	ds_read_b128 v[194:197], v33 offset:11264
	ds_read_b128 v[198:201], v33 offset:12288
	ds_read_b128 v[202:205], v33 offset:13312
	ds_read_b128 v[206:209], v33 offset:14336
	ds_read_b128 v[210:213], v33 offset:15360
	s_add_i32 s0, s31, 1
	v_cvt_pk_bf16_f32 v214, v14, v15
	v_cvt_pk_bf16_f32 v215, v16, v17
	v_cvt_pk_bf16_f32 v216, v10, v11
	v_cvt_pk_bf16_f32 v217, v12, v13
	v_cvt_pk_bf16_f32 v218, v2, v3
	v_cvt_pk_bf16_f32 v219, v4, v5
	s_waitcnt lgkmcnt(14)
	v_mfma_f32_16x16x32_bf16 v[92:95], v[92:95], v[214:217], 0
	v_cvt_pk_bf16_f32 v220, v6, v7
	v_cvt_pk_bf16_f32 v221, v8, v9
	v_lshlrev_b32_e32 v33, 16, v50
	v_and_b32_e32 v50, 0xffff0000, v50
	v_mfma_f32_16x16x32_bf16 v[92:95], v[96:99], v[218:221], v[92:95]
	s_bitcmp0_b32 s31, 0
	s_cselect_b32 s1, s29, 0x20200
	s_nop 0
	v_pk_mul_f32 v[16:17], v[16:17], v[34:35] op_sel_hi:[1,0]
	v_mfma_f32_16x16x32_bf16 v[96:99], v[100:103], v[214:217], 0
	v_lshlrev_b32_e32 v100, 16, v51
	v_and_b32_e32 v51, 0xffff0000, v51
	s_nop 0
	v_sub_f32_e32 v33, v33, v92
	v_mfma_f32_16x16x32_bf16 v[96:99], v[104:107], v[218:221], v[96:99]
	v_sub_f32_e32 v105, v100, v94
	v_sub_f32_e32 v104, v51, v95
	v_sub_f32_e32 v106, v50, v93
	v_mfma_f32_16x16x32_bf16 v[100:103], v[108:111], v[214:217], 0
	v_lshlrev_b32_e32 v107, 16, v48
	s_nop 2
	v_sub_f32_e32 v107, v107, v96
	v_lshlrev_b32_e32 v109, 16, v46
	v_mfma_f32_16x16x32_bf16 v[92:95], v[112:115], v[218:221], v[100:103]
	v_and_b32_e32 v46, 0xffff0000, v46
	v_lshlrev_b32_e32 v110, 16, v47
	v_and_b32_e32 v47, 0xffff0000, v47
	v_and_b32_e32 v100, 0xffff0000, v48
	v_and_b32_e32 v102, 0xffff0000, v49
	v_lshlrev_b32_e32 v101, 16, v49
	v_sub_f32_e32 v103, v102, v99
	v_sub_f32_e32 v102, v100, v97
	v_mfma_f32_16x16x32_bf16 v[48:51], v[116:119], v[214:217], 0
	v_sub_f32_e32 v108, v101, v98
	v_cvt_pk_bf16_f32 v100, v33, v106
	v_cvt_pk_bf16_f32 v101, v105, v104
	v_cvt_pk_bf16_f32 v102, v107, v102
	v_mfma_f32_16x16x32_bf16 v[104:107], v[132:135], v[214:217], 0
	v_cvt_pk_bf16_f32 v103, v108, v103
	v_sub_f32_e32 v33, v47, v95
	v_sub_f32_e32 v108, v110, v94
	v_mfma_f32_16x16x32_bf16 v[48:51], v[120:123], v[218:221], v[48:51]
	v_sub_f32_e32 v110, v46, v93
	v_sub_f32_e32 v109, v109, v92
	v_lshlrev_b32_e32 v111, 16, v44
	v_mfma_f32_16x16x32_bf16 v[96:99], v[124:127], v[214:217], 0
	v_and_b32_e32 v112, 0xffff0000, v44
	v_and_b32_e32 v44, 0xffff0000, v45
	v_pk_mul_f32 v[14:15], v[14:15], v[34:35] op_sel_hi:[1,0]
	v_mfma_f32_16x16x32_bf16 v[92:95], v[136:139], v[218:221], v[104:107]
	v_mul_f32_e64 v12, v12, v34
	v_mul_f32_e64 v13, v13, v34
	v_pk_mul_f32 v[10:11], v[10:11], v[34:35] op_sel_hi:[1,0]
	v_pk_mul_f32 v[4:5], v[4:5], v[34:35] op_sel_hi:[1,0]
	v_lshlrev_b32_e32 v104, 16, v45
	v_mfma_f32_16x16x32_bf16 v[96:99], v[128:131], v[218:221], v[96:99]
	v_sub_f32_e32 v105, v44, v51
	v_pk_mul_f32 v[2:3], v[2:3], v[34:35] op_sel_hi:[1,0]
	v_pk_mul_f32 v[8:9], v[8:9], v[34:35] op_sel_hi:[1,0]
	s_waitcnt lgkmcnt(12)
	v_mfma_f32_16x16x32_bf16 v[44:47], v[160:163], v[100:103], v[92:95]
	v_mul_f32_e64 v6, v6, v34
	v_mul_f32_e64 v7, v7, v34
	v_lshl_add_u64 v[30:31], v[30:31], 0, s[16:17]
	s_mov_b32 s31, s0
	v_sub_f32_e32 v95, v104, v50
	v_sub_f32_e32 v94, v112, v49
	v_sub_f32_e32 v104, v111, v48
	v_mfma_f32_16x16x32_bf16 v[48:51], v[140:143], v[214:217], 0
	v_cvt_pk_bf16_f32 v94, v104, v94
	v_cvt_pk_bf16_f32 v95, v95, v105
	v_cvt_pk_bf16_f32 v93, v108, v33
	v_mfma_f32_16x16x32_bf16 v[96:99], v[156:159], v[100:103], v[96:99]
	v_add_u32_e32 v33, s1, v21
	v_cvt_pk_bf16_f32 v92, v109, v110
	s_add_i32 s1, s30, 1
	v_mfma_f32_16x16x32_bf16 v[48:51], v[144:147], v[218:221], v[48:51]
	s_cmp_lg_u32 s30, 3
	s_nop 2
	v_cvt_pk_bf16_f32 v34, v96, s0
	v_add_u32_e32 v96, v33, v74
	v_mfma_f32_16x16x32_bf16 v[104:107], v[148:151], v[214:217], 0
	ds_write_b16 v96, v34
	v_cvt_pk_bf16_f32 v34, v97, s0
	v_add_u32_e32 v96, v33, v75
	s_waitcnt lgkmcnt(12)
	v_mfma_f32_16x16x32_bf16 v[48:51], v[166:169], v[100:103], v[48:51]
	ds_write_b16 v96, v34
	v_cvt_pk_bf16_f32 v34, v98, s0
	v_add_u32_e32 v96, v33, v76
	v_mfma_f32_16x16x32_bf16 v[104:107], v[152:155], v[218:221], v[104:107]
	ds_write_b16 v96, v34
	v_cvt_pk_bf16_f32 v34, v99, s0
	v_add_u32_e32 v96, v33, v77
	s_waitcnt lgkmcnt(13)
	v_mfma_f32_16x16x32_bf16 v[48:51], v[170:173], v[92:95], v[48:51]
	ds_write_b16 v96, v34
	v_cvt_pk_bf16_f32 v34, v44, s0
	v_add_u32_e32 v44, v33, v78
	s_waitcnt lgkmcnt(13)
	v_mfma_f32_16x16x32_bf16 v[104:107], v[174:177], v[100:103], v[104:107]
	ds_write_b16 v44, v34
	v_cvt_pk_bf16_f32 v34, v45, s0
	v_add_u32_e32 v44, v33, v79
	ds_write_b16 v44, v34
	v_cvt_pk_bf16_f32 v34, v46, s0
	v_add_u32_e32 v44, v33, v80
	ds_write_b16 v44, v34
	v_cvt_pk_bf16_f32 v34, v47, s0
	v_add_u32_e32 v44, v33, v81
	s_waitcnt lgkmcnt(14)
	v_mfma_f32_16x16x32_bf16 v[104:107], v[178:181], v[92:95], v[104:107]
	ds_write_b16 v44, v34
	v_cvt_pk_bf16_f32 v34, v48, s0
	v_add_u32_e32 v44, v33, v82
	ds_write_b16 v44, v34
	v_cvt_pk_bf16_f32 v34, v49, s0
	v_add_u32_e32 v44, v33, v83
	ds_write_b16 v44, v34
	v_cvt_pk_bf16_f32 v34, v50, s0
	v_add_u32_e32 v44, v33, v84
	ds_write_b16 v44, v34
	v_cvt_pk_bf16_f32 v34, v51, s0
	v_add_u32_e32 v44, v33, v85
	ds_write_b16 v44, v34
	v_cvt_pk_bf16_f32 v34, v104, s0
	v_add_u32_e32 v44, v33, v86
	v_mfma_f32_16x16x32_bf16 v[14:17], v[182:185], v[100:103], v[14:17]
	ds_write_b16 v44, v34
	v_cvt_pk_bf16_f32 v34, v105, s0
	v_add_u32_e32 v44, v33, v87
	s_waitcnt lgkmcnt(14)
	v_mfma_f32_16x16x32_bf16 v[10:13], v[190:193], v[100:103], v[10:13]
	ds_write_b16 v44, v34
	v_cvt_pk_bf16_f32 v34, v106, s0
	v_add_u32_e32 v44, v33, v88
	v_mfma_f32_16x16x32_bf16 v[2:5], v[198:201], v[100:103], v[2:5]
	ds_write_b16 v44, v34
	v_cvt_pk_bf16_f32 v34, v107, s0
	v_add_u32_e32 v33, v33, v89
	v_mfma_f32_16x16x32_bf16 v[6:9], v[206:209], v[100:103], v[6:9]
	ds_write_b16 v33, v34
	s_waitcnt lgkmcnt(0)
	s_cselect_b32 s30, s1, 0
	v_mfma_f32_16x16x32_bf16 v[14:17], v[186:189], v[92:95], v[14:17]
	s_barrier
; #define LAS __attribute__((address_space(3)))
; __device__ __forceinline__ void scan_prompt_wg(const Params& P, LAS unsigned char* lds, int s, int h, int wave, int lane) {
;     ...
;         for (int n = 0; n < NST; ++n) {
;             const LAS unsigned char* ops = lds + slot * SR_SLOT;
;             const float gtn = (n + 1 < NST) ? GT[(size_t)(n + 1) * 8] : 0.f;
;             v2u uc[4];
; #pragma unroll
;             for (int tau = 0; tau < 4; ++tau) uc[tau] = (n + 2 < NST) ? (Ug + (size_t)(n + 2) * (step_stride / 8))[tau * 64] : (v2u){0u, 0u};
;     ...
;             gt = gtn;
; #pragma unroll
;             for (int tau = 0; tau < 4; ++tau) { ua[tau] = ub[tau]; ub[tau] = uc[tau]; }
;             slot = (slot == SR_NS - 1) ? 0 : slot + 1;
	v_mfma_f32_16x16x32_bf16 v[10:13], v[194:197], v[92:95], v[10:13]
	s_add_u32 s14, s14, 32
	s_addc_u32 s15, s15, 0
	s_cmpk_eq_i32 s0, 0x80
	v_mfma_f32_16x16x32_bf16 v[2:5], v[202:205], v[92:95], v[2:5]
	v_mov_b64_e32 v[50:51], v[42:43]
	v_mov_b64_e32 v[48:49], v[40:41]
	v_mov_b64_e32 v[46:47], v[38:39]
	s_waitcnt lgkmcnt(14)
	v_mfma_f32_16x16x32_bf16 v[6:9], v[210:213], v[92:95], v[6:9]
	v_mov_b64_e32 v[44:45], v[36:37]
	s_nop 0
	s_cbranch_scc1 .LBB0_653
.LBB0_643:
	s_waitcnt vmcnt(0)
	v_mov_b32_e32 v34, v91
	v_mov_b64_e32 v[36:37], v[28:29]
	v_mov_b64_e32 v[38:39], v[26:27]
	v_mov_b64_e32 v[40:41], v[24:25]
	v_mov_b64_e32 v[42:43], v[22:23]
	s_cmpk_eq_i32 s31, 0x7f
	v_mov_b32_e32 v91, 0
	s_cbranch_scc1 .LBB0_645
	global_load_dword v91, v165, s[14:15]
